# GEMM unit headers: v_cndmask+v_cmp_ne ballot of a wave-uniform flag replaced by s_andn2_b64 (3 sites), on top of v31
# baseline (speedup 1.0000x reference)
; template <class Epi>
; __device__ __forceinline__ void gemm_phase(LAS unsigned char* lds, const GemmD g, const Epi& E, int G, int c) {
;     ...
;         const bool has_next = unit_at(g, G, c, ui + 1, npm, npn, nz);
;         const char* nA = has_next ? PG8_APTR(nz, npm) : cA; const char* nB = has_next ? PG8_BPTR(nz, npn) : cB;
.LBB0_101:
	s_andn2_b64 s[44:45], exec, s[4:5]
	s_andn2_b64 vcc, exec, s[4:5]
	s_mov_b64 s[84:85], s[46:47]
	s_cbranch_vccnz .LBB0_103
	s_mul_i32 s5, s19, 0x2c0000
	s_mul_hi_i32 s4, s19, 0x2c0000
	s_add_u32 s84, s62, s5
	s_addc_u32 s85, s63, s4

; template <class Epi>
; __device__ __forceinline__ void gemm_phase(LAS unsigned char* lds, const GemmD g, const Epi& E, int G, int c) {
;     ...
;         const bool has_next = unit_at(g, G, c, ui + 1, npm, npn, nz);
;         const char* nA = has_next ? PG8_APTR(nz, npm) : cA; const char* nB = has_next ? PG8_BPTR(nz, npn) : cB;
.LBB0_292:
	s_andn2_b64 s[44:45], exec, s[4:5]
	s_andn2_b64 vcc, exec, s[4:5]
	s_mov_b64 s[66:67], s[82:83]
	s_cbranch_vccnz .LBB0_294
	s_ashr_i32 s4, s22, 31
	s_lshr_b32 s4, s4, 30
	s_add_i32 s28, s22, s4
	s_ashr_i32 s4, s28, 2
	s_and_b32 s28, s28, -4
	s_sub_i32 s28, s22, s28
	s_ashr_i32 s5, s4, 31
	s_ashr_i32 s29, s28, 31
	s_ashr_i32 s63, s62, 31
	s_lshl_b64 s[30:31], s[62:63], 20
	s_lshl_b64 s[28:29], s[28:29], 23
	s_lshl_b64 s[4:5], s[4:5], 25
	s_add_u32 s28, s14, s28
	s_addc_u32 s29, s15, s29
	s_add_u32 s4, s28, s4
	s_addc_u32 s5, s29, s5
	s_add_u32 s66, s4, s30
	s_addc_u32 s67, s5, s31

; template <class Epi>
; __device__ __forceinline__ void gemm_phase(LAS unsigned char* lds, const GemmD g, const Epi& E, int G, int c) {
;     ...
;         const bool has_next = unit_at(g, G, c, ui + 1, npm, npn, nz);
;         const char* nA = has_next ? PG8_APTR(nz, npm) : cA; const char* nB = has_next ? PG8_BPTR(nz, npn) : cB;
.LBB0_324:
	s_andn2_b64 s[42:43], exec, s[4:5]
	s_andn2_b64 vcc, exec, s[4:5]
	s_mov_b64 s[66:67], s[84:85]
	s_cbranch_vccnz .LBB0_326
	s_ashr_i32 s4, s54, 31
	s_lshr_b32 s4, s4, 30
	s_add_i32 s17, s54, s4
	s_ashr_i32 s4, s17, 2
	s_and_b32 s17, s17, -4
	s_sub_i32 s28, s54, s17
	s_ashr_i32 s5, s4, 31
	s_ashr_i32 s29, s28, 31
	s_ashr_i32 s61, s60, 31
	s_lshl_b64 s[38:39], s[60:61], 19
	s_lshl_b64 s[28:29], s[28:29], 9
	s_lshl_b64 s[4:5], s[4:5], 22
	s_add_u32 s17, s76, s28
	s_addc_u32 s19, s77, s29
	s_add_u32 s4, s17, s4
	s_addc_u32 s5, s19, s5
	s_add_u32 s66, s4, s38
	s_addc_u32 s67, s5, s39
